# peeled first K iteration (srcC=0, no accumulator zeroing) also for w_in, fp8 down, bf16 down, w_out full-mode loops
# baseline (speedup 1.0000x reference)
.LBB0_461:
	s_add_u32 s11, s24, 0x100
	s_addc_u32 s13, s25, 0
	s_mov_b32 s42, -2
.LPF_462:
	s_add_u32 s24, s26, 0x100
	s_addc_u32 s25, s27, 0
	s_add_i32 s43, 0, 0x10000
	s_cmp_eq_u32 s42, 40
	s_cselect_b32 s31, s21, s25
	s_cselect_b32 s30, s20, s24
	s_cselect_b32 s29, s23, s13
	s_cselect_b32 s28, s22, s11
	s_add_i32 s60, 0, 0x14000
	v_add_u32_e32 v2, s43, v187
	v_add_u32_e32 v14, s60, v187
	ds_read_b128 v[18:21], v2
	ds_read_b128 v[22:25], v2 offset:1024
	ds_read_b128 v[26:29], v2 offset:2048
	ds_read_b128 v[30:33], v2 offset:3072
	ds_read_b128 v[2:5], v14
	ds_read_b128 v[6:9], v14 offset:1024
	ds_read_b128 v[10:13], v14 offset:2048
	ds_read_b128 v[14:17], v14 offset:3072
	v_lshl_add_u64 v[182:183], s[26:27], 0, v[170:171]
	s_add_i32 m0, s39, 0xc000
	ds_read_b128 v[174:177], v188
	ds_read_b128 v[178:181], v188 offset:1024
	ds_read_b128 v[190:193], v188 offset:2048
	ds_read_b128 v[194:197], v188 offset:3072
	ds_read_b128 v[206:209], v188 offset:4096
	ds_read_b128 v[210:213], v188 offset:5120
	ds_read_b128 v[214:217], v188 offset:6144
	ds_read_b128 v[218:221], v188 offset:7168
	global_load_lds_dwordx4 v[182:183], off
	v_lshl_add_u64 v[182:183], s[26:27], 0, v[172:173]
	s_add_i32 m0, s39, 0xe000
	s_nop 0
	global_load_lds_dwordx4 v[182:183], off
	s_waitcnt vmcnt(8)
	s_waitcnt lgkmcnt(0)
	s_setprio 1
	s_barrier
	v_mfma_scale_f32_16x16x128_f8f6f4 v[160:163], v[18:25], v[174:181], 0, v186, v186 op_sel_hi:[0,0,0]
	v_mfma_scale_f32_16x16x128_f8f6f4 v[156:159], v[26:33], v[174:181], 0, v186, v186 op_sel_hi:[0,0,0]
	v_mfma_scale_f32_16x16x128_f8f6f4 v[144:147], v[18:25], v[190:197], 0, v186, v186 op_sel_hi:[0,0,0]
	v_mfma_scale_f32_16x16x128_f8f6f4 v[140:143], v[26:33], v[190:197], 0, v186, v186 op_sel_hi:[0,0,0]
	v_mfma_scale_f32_16x16x128_f8f6f4 v[128:131], v[18:25], v[206:213], 0, v186, v186 op_sel_hi:[0,0,0]
	v_mfma_scale_f32_16x16x128_f8f6f4 v[124:127], v[26:33], v[206:213], 0, v186, v186 op_sel_hi:[0,0,0]
	v_mfma_scale_f32_16x16x128_f8f6f4 v[112:115], v[18:25], v[214:221], 0, v186, v186 op_sel_hi:[0,0,0]
	v_mfma_scale_f32_16x16x128_f8f6f4 v[108:111], v[26:33], v[214:221], 0, v186, v186 op_sel_hi:[0,0,0]
	v_mfma_scale_f32_16x16x128_f8f6f4 v[152:155], v[2:9], v[174:181], 0, v186, v186 op_sel_hi:[0,0,0]
	v_mfma_scale_f32_16x16x128_f8f6f4 v[148:151], v[10:17], v[174:181], 0, v186, v186 op_sel_hi:[0,0,0]
	v_mfma_scale_f32_16x16x128_f8f6f4 v[136:139], v[2:9], v[190:197], 0, v186, v186 op_sel_hi:[0,0,0]
	v_mfma_scale_f32_16x16x128_f8f6f4 v[132:135], v[10:17], v[190:197], 0, v186, v186 op_sel_hi:[0,0,0]
	v_mfma_scale_f32_16x16x128_f8f6f4 v[120:123], v[2:9], v[206:213], 0, v186, v186 op_sel_hi:[0,0,0]
	v_mfma_scale_f32_16x16x128_f8f6f4 v[116:119], v[10:17], v[206:213], 0, v186, v186 op_sel_hi:[0,0,0]
	v_mfma_scale_f32_16x16x128_f8f6f4 v[104:107], v[2:9], v[214:221], 0, v186, v186 op_sel_hi:[0,0,0]
	v_mfma_scale_f32_16x16x128_f8f6f4 v[100:103], v[10:17], v[214:221], 0, v186, v186 op_sel_hi:[0,0,0]
	s_barrier
	s_setprio 0
	s_add_i32 s26, s43, s38
	v_lshl_add_u64 v[174:175], s[28:29], 0, v[34:35]
	s_mov_b32 m0, s26
	ds_read_b128 v[190:193], v188 offset:16384
	ds_read_b128 v[194:197], v188 offset:17408
	ds_read_b128 v[206:209], v188 offset:18432
	ds_read_b128 v[210:213], v188 offset:19456
	ds_read_b128 v[214:217], v188 offset:20480
	ds_read_b128 v[218:221], v188 offset:21504
	ds_read_b128 v[240:243], v188 offset:22528
	ds_read_b128 v[244:247], v188 offset:23552
	global_load_lds_dwordx4 v[174:175], off
	s_add_i32 m0, s26, 0x2000
	s_add_u32 s26, s28, 0xb0000
	v_lshl_add_u64 v[176:177], s[28:29], 0, v[168:169]
	s_addc_u32 s27, s29, 0
	s_add_i32 s43, s60, s38
	global_load_lds_dwordx4 v[176:177], off
	v_lshl_add_u64 v[178:179], s[26:27], 0, v[34:35]
	s_mov_b32 m0, s43
	v_lshl_add_u64 v[180:181], s[30:31], 0, v[166:167]
	global_load_lds_dwordx4 v[178:179], off
	v_lshl_add_u64 v[178:179], s[26:27], 0, v[168:169]
	s_add_i32 m0, s43, 0x2000
	s_nop 0
	global_load_lds_dwordx4 v[178:179], off
	v_lshl_add_u64 v[178:179], s[30:31], 0, v[164:165]
	s_mov_b32 m0, s39
	s_nop 0
	global_load_lds_dwordx4 v[178:179], off
	s_mov_b32 m0, s44
	s_nop 0
	global_load_lds_dwordx4 v[180:181], off
	s_waitcnt vmcnt(8)
	s_waitcnt lgkmcnt(0)
	s_setprio 1
	s_barrier
	v_mfma_scale_f32_16x16x128_f8f6f4 v[96:99], v[18:25], v[190:197], 0, v186, v186 op_sel_hi:[0,0,0]
	v_mfma_scale_f32_16x16x128_f8f6f4 v[92:95], v[26:33], v[190:197], 0, v186, v186 op_sel_hi:[0,0,0]
	v_mfma_scale_f32_16x16x128_f8f6f4 v[80:83], v[18:25], v[206:213], 0, v186, v186 op_sel_hi:[0,0,0]
	v_mfma_scale_f32_16x16x128_f8f6f4 v[76:79], v[26:33], v[206:213], 0, v186, v186 op_sel_hi:[0,0,0]
	v_mfma_scale_f32_16x16x128_f8f6f4 v[64:67], v[18:25], v[214:221], 0, v186, v186 op_sel_hi:[0,0,0]
	v_mfma_scale_f32_16x16x128_f8f6f4 v[60:63], v[26:33], v[214:221], 0, v186, v186 op_sel_hi:[0,0,0]
	v_mfma_scale_f32_16x16x128_f8f6f4 v[48:51], v[18:25], v[240:247], 0, v186, v186 op_sel_hi:[0,0,0]
	v_mfma_scale_f32_16x16x128_f8f6f4 v[44:47], v[26:33], v[240:247], 0, v186, v186 op_sel_hi:[0,0,0]
	v_mfma_scale_f32_16x16x128_f8f6f4 v[88:91], v[2:9], v[190:197], 0, v186, v186 op_sel_hi:[0,0,0]
	v_mfma_scale_f32_16x16x128_f8f6f4 v[84:87], v[10:17], v[190:197], 0, v186, v186 op_sel_hi:[0,0,0]
	v_mfma_scale_f32_16x16x128_f8f6f4 v[72:75], v[2:9], v[206:213], 0, v186, v186 op_sel_hi:[0,0,0]
	v_mfma_scale_f32_16x16x128_f8f6f4 v[68:71], v[10:17], v[206:213], 0, v186, v186 op_sel_hi:[0,0,0]
	v_mfma_scale_f32_16x16x128_f8f6f4 v[56:59], v[2:9], v[214:221], 0, v186, v186 op_sel_hi:[0,0,0]
	v_mfma_scale_f32_16x16x128_f8f6f4 v[52:55], v[10:17], v[214:221], 0, v186, v186 op_sel_hi:[0,0,0]
	v_mfma_scale_f32_16x16x128_f8f6f4 v[40:43], v[2:9], v[240:247], 0, v186, v186 op_sel_hi:[0,0,0]
	v_mfma_scale_f32_16x16x128_f8f6f4 v[36:39], v[10:17], v[240:247], 0, v186, v186 op_sel_hi:[0,0,0]
	s_barrier
	s_setprio 0
	s_add_i32 s43, 0, 0x18000
	s_add_i32 s60, 0, 0x1c000
	v_add_u32_e32 v14, s43, v187
	v_add_u32_e32 v30, s60, v187
	ds_read_b128 v[2:5], v14
	ds_read_b128 v[6:9], v14 offset:1024
	ds_read_b128 v[10:13], v14 offset:2048
	ds_read_b128 v[14:17], v14 offset:3072
	ds_read_b128 v[18:21], v30
	ds_read_b128 v[22:25], v30 offset:1024
	ds_read_b128 v[26:29], v30 offset:2048
	ds_read_b128 v[30:33], v30 offset:3072
	s_add_u32 s26, s30, 0xb0000
	s_addc_u32 s27, s31, 0
	s_mov_b32 m0, s45
	v_lshl_add_u64 v[182:183], s[26:27], 0, v[164:165]
	ds_read_b128 v[190:193], v188 offset:32768
	ds_read_b128 v[194:197], v188 offset:33792
	ds_read_b128 v[206:209], v188 offset:34816
	ds_read_b128 v[210:213], v188 offset:35840
	ds_read_b128 v[214:217], v188 offset:36864
	ds_read_b128 v[218:221], v188 offset:37888
	ds_read_b128 v[240:243], v188 offset:38912
	ds_read_b128 v[244:247], v188 offset:39936
	global_load_lds_dwordx4 v[182:183], off
	v_lshl_add_u64 v[182:183], s[26:27], 0, v[166:167]
	s_mov_b32 m0, s46
	s_nop 0
	global_load_lds_dwordx4 v[182:183], off
	s_waitcnt vmcnt(8)
	s_waitcnt lgkmcnt(0)
	s_setprio 1
	s_barrier
	v_mfma_scale_f32_16x16x128_f8f6f4 v[160:163], v[2:9], v[190:197], v[160:163], v186, v186 op_sel_hi:[0,0,0]
	v_mfma_scale_f32_16x16x128_f8f6f4 v[156:159], v[10:17], v[190:197], v[156:159], v186, v186 op_sel_hi:[0,0,0]
	v_mfma_scale_f32_16x16x128_f8f6f4 v[144:147], v[2:9], v[206:213], v[144:147], v186, v186 op_sel_hi:[0,0,0]
	v_mfma_scale_f32_16x16x128_f8f6f4 v[140:143], v[10:17], v[206:213], v[140:143], v186, v186 op_sel_hi:[0,0,0]
	v_mfma_scale_f32_16x16x128_f8f6f4 v[128:131], v[2:9], v[214:221], v[128:131], v186, v186 op_sel_hi:[0,0,0]
	v_mfma_scale_f32_16x16x128_f8f6f4 v[124:127], v[10:17], v[214:221], v[124:127], v186, v186 op_sel_hi:[0,0,0]
	v_mfma_scale_f32_16x16x128_f8f6f4 v[112:115], v[2:9], v[240:247], v[112:115], v186, v186 op_sel_hi:[0,0,0]
	v_mfma_scale_f32_16x16x128_f8f6f4 v[108:111], v[10:17], v[240:247], v[108:111], v186, v186 op_sel_hi:[0,0,0]
	v_mfma_scale_f32_16x16x128_f8f6f4 v[152:155], v[18:25], v[190:197], v[152:155], v186, v186 op_sel_hi:[0,0,0]
	v_mfma_scale_f32_16x16x128_f8f6f4 v[148:151], v[26:33], v[190:197], v[148:151], v186, v186 op_sel_hi:[0,0,0]
	v_mfma_scale_f32_16x16x128_f8f6f4 v[136:139], v[18:25], v[206:213], v[136:139], v186, v186 op_sel_hi:[0,0,0]
	v_mfma_scale_f32_16x16x128_f8f6f4 v[132:135], v[26:33], v[206:213], v[132:135], v186, v186 op_sel_hi:[0,0,0]
	v_mfma_scale_f32_16x16x128_f8f6f4 v[120:123], v[18:25], v[214:221], v[120:123], v186, v186 op_sel_hi:[0,0,0]
	v_mfma_scale_f32_16x16x128_f8f6f4 v[116:119], v[26:33], v[214:221], v[116:119], v186, v186 op_sel_hi:[0,0,0]
	v_mfma_scale_f32_16x16x128_f8f6f4 v[104:107], v[18:25], v[240:247], v[104:107], v186, v186 op_sel_hi:[0,0,0]
	v_mfma_scale_f32_16x16x128_f8f6f4 v[100:103], v[26:33], v[240:247], v[100:103], v186, v186 op_sel_hi:[0,0,0]
	s_barrier
	s_setprio 0
	s_add_i32 s26, s43, s38
	v_lshl_add_u64 v[174:175], v[174:175], 0, s[18:19]
	s_mov_b32 m0, s26
	ds_read_b128 v[190:193], v188 offset:49152
	ds_read_b128 v[194:197], v188 offset:50176
	ds_read_b128 v[206:209], v188 offset:51200
	ds_read_b128 v[210:213], v188 offset:52224
	ds_read_b128 v[214:217], v188 offset:53248
	ds_read_b128 v[218:221], v188 offset:54272
	ds_read_b128 v[240:243], v188 offset:55296
	ds_read_b128 v[244:247], v188 offset:56320
	global_load_lds_dwordx4 v[174:175], off
	s_add_i32 m0, s26, 0x2000
	s_add_u32 s26, s28, 0xb0080
	v_lshl_add_u64 v[174:175], v[176:177], 0, s[18:19]
	s_addc_u32 s27, s29, 0
	s_add_i32 s28, s60, s38
	global_load_lds_dwordx4 v[174:175], off
	v_lshl_add_u64 v[174:175], s[26:27], 0, v[34:35]
	s_mov_b32 m0, s28
	s_nop 0
	global_load_lds_dwordx4 v[174:175], off
	v_lshl_add_u64 v[174:175], s[26:27], 0, v[168:169]
	s_add_i32 m0, s28, 0x2000
	s_nop 0
	global_load_lds_dwordx4 v[174:175], off
	v_lshl_add_u64 v[174:175], v[178:179], 0, s[18:19]
	s_mov_b32 m0, s47
	s_nop 0
	global_load_lds_dwordx4 v[174:175], off
	v_lshl_add_u64 v[174:175], v[180:181], 0, s[18:19]
	s_mov_b32 m0, s52
	s_nop 0
	global_load_lds_dwordx4 v[174:175], off
	s_waitcnt vmcnt(8)
	s_waitcnt lgkmcnt(0)
	s_setprio 1
	s_barrier
	v_mfma_scale_f32_16x16x128_f8f6f4 v[96:99], v[2:9], v[190:197], v[96:99], v186, v186 op_sel_hi:[0,0,0]
	v_mfma_scale_f32_16x16x128_f8f6f4 v[92:95], v[10:17], v[190:197], v[92:95], v186, v186 op_sel_hi:[0,0,0]
	v_mfma_scale_f32_16x16x128_f8f6f4 v[80:83], v[2:9], v[206:213], v[80:83], v186, v186 op_sel_hi:[0,0,0]
	v_mfma_scale_f32_16x16x128_f8f6f4 v[76:79], v[10:17], v[206:213], v[76:79], v186, v186 op_sel_hi:[0,0,0]
	v_mfma_scale_f32_16x16x128_f8f6f4 v[64:67], v[2:9], v[214:221], v[64:67], v186, v186 op_sel_hi:[0,0,0]
	v_mfma_scale_f32_16x16x128_f8f6f4 v[60:63], v[10:17], v[214:221], v[60:63], v186, v186 op_sel_hi:[0,0,0]
	v_mfma_scale_f32_16x16x128_f8f6f4 v[48:51], v[2:9], v[240:247], v[48:51], v186, v186 op_sel_hi:[0,0,0]
	v_mfma_scale_f32_16x16x128_f8f6f4 v[44:47], v[10:17], v[240:247], v[44:47], v186, v186 op_sel_hi:[0,0,0]
	v_mfma_scale_f32_16x16x128_f8f6f4 v[88:91], v[18:25], v[190:197], v[88:91], v186, v186 op_sel_hi:[0,0,0]
	v_mfma_scale_f32_16x16x128_f8f6f4 v[84:87], v[26:33], v[190:197], v[84:87], v186, v186 op_sel_hi:[0,0,0]
	v_mfma_scale_f32_16x16x128_f8f6f4 v[72:75], v[18:25], v[206:213], v[72:75], v186, v186 op_sel_hi:[0,0,0]
	v_mfma_scale_f32_16x16x128_f8f6f4 v[68:71], v[26:33], v[206:213], v[68:71], v186, v186 op_sel_hi:[0,0,0]
	v_mfma_scale_f32_16x16x128_f8f6f4 v[56:59], v[18:25], v[214:221], v[56:59], v186, v186 op_sel_hi:[0,0,0]
	v_mfma_scale_f32_16x16x128_f8f6f4 v[52:55], v[26:33], v[214:221], v[52:55], v186, v186 op_sel_hi:[0,0,0]
	v_mfma_scale_f32_16x16x128_f8f6f4 v[40:43], v[18:25], v[240:247], v[40:43], v186, v186 op_sel_hi:[0,0,0]
	v_mfma_scale_f32_16x16x128_f8f6f4 v[36:39], v[26:33], v[240:247], v[36:39], v186, v186 op_sel_hi:[0,0,0]
	s_barrier
	s_setprio 0
	s_add_i32 s42, s42, 2
	s_add_u32 s11, s11, 0x100
	s_addc_u32 s13, s13, 0
	s_cmp_gt_u32 s42, 41
	s_mov_b64 s[26:27], s[24:25]
	s_cbranch_scc0 .LBB0_462

.LBB0_545:
	s_add_u32 s11, s26, 0x100
	s_addc_u32 s13, s27, 0
	s_mov_b32 s42, -2
.LPD_546:
	s_add_u32 s26, s24, 0x100
	s_addc_u32 s27, s25, 0
	s_add_i32 s43, 0, 0x10000
	s_cmpk_eq_i32 s42, 0x54
	s_cselect_b32 s31, s21, s27
	s_cselect_b32 s30, s20, s26
	s_cselect_b32 s29, s23, s13
	s_cselect_b32 s28, s22, s11
	s_add_i32 s60, 0, 0x14000
	v_add_u32_e32 v144, s43, v186
	v_add_u32_e32 v170, s60, v186
	ds_read_b128 v[132:135], v144
	ds_read_b128 v[136:139], v144 offset:1024
	ds_read_b128 v[140:143], v144 offset:2048
	ds_read_b128 v[144:147], v144 offset:3072
	ds_read_b128 v[148:151], v170
	ds_read_b128 v[152:155], v170 offset:1024
	ds_read_b128 v[156:159], v170 offset:2048
	ds_read_b128 v[170:173], v170 offset:3072
	v_lshl_add_u64 v[182:183], s[24:25], 0, v[166:167]
	s_add_i32 m0, s39, 0xc000
	ds_read_b128 v[174:177], v187
	ds_read_b128 v[178:181], v187 offset:1024
	ds_read_b128 v[188:191], v187 offset:2048
	ds_read_b128 v[192:195], v187 offset:3072
	ds_read_b128 v[206:209], v187 offset:4096
	ds_read_b128 v[210:213], v187 offset:5120
	ds_read_b128 v[214:217], v187 offset:6144
	ds_read_b128 v[218:221], v187 offset:7168
	global_load_lds_dwordx4 v[182:183], off
	v_lshl_add_u64 v[182:183], s[24:25], 0, v[168:169]
	s_add_i32 m0, s39, 0xe000
	s_nop 0
	global_load_lds_dwordx4 v[182:183], off
	s_waitcnt vmcnt(8)
	s_waitcnt lgkmcnt(0)
	s_setprio 1
	s_barrier
	v_mfma_f32_16x16x32_bf16 v[128:131], v[132:135], v[174:177], 0
	v_mfma_f32_16x16x32_bf16 v[128:131], v[136:139], v[178:181], v[128:131]
	v_mfma_f32_16x16x32_bf16 v[124:127], v[140:143], v[174:177], 0
	v_mfma_f32_16x16x32_bf16 v[124:127], v[144:147], v[178:181], v[124:127]
	v_mfma_f32_16x16x32_bf16 v[112:115], v[132:135], v[188:191], 0
	v_mfma_f32_16x16x32_bf16 v[112:115], v[136:139], v[192:195], v[112:115]
	v_mfma_f32_16x16x32_bf16 v[108:111], v[140:143], v[188:191], 0
	v_mfma_f32_16x16x32_bf16 v[108:111], v[144:147], v[192:195], v[108:111]
	v_mfma_f32_16x16x32_bf16 v[96:99], v[132:135], v[206:209], 0
	v_mfma_f32_16x16x32_bf16 v[96:99], v[136:139], v[210:213], v[96:99]
	v_mfma_f32_16x16x32_bf16 v[92:95], v[140:143], v[206:209], 0
	v_mfma_f32_16x16x32_bf16 v[92:95], v[144:147], v[210:213], v[92:95]
	v_mfma_f32_16x16x32_bf16 v[80:83], v[132:135], v[214:217], 0
	v_mfma_f32_16x16x32_bf16 v[80:83], v[136:139], v[218:221], v[80:83]
	v_mfma_f32_16x16x32_bf16 v[76:79], v[140:143], v[214:217], 0
	v_mfma_f32_16x16x32_bf16 v[76:79], v[144:147], v[218:221], v[76:79]
	v_mfma_f32_16x16x32_bf16 v[120:123], v[148:151], v[174:177], 0
	v_mfma_f32_16x16x32_bf16 v[120:123], v[152:155], v[178:181], v[120:123]
	v_mfma_f32_16x16x32_bf16 v[116:119], v[156:159], v[174:177], 0
	v_mfma_f32_16x16x32_bf16 v[116:119], v[170:173], v[178:181], v[116:119]
	v_mfma_f32_16x16x32_bf16 v[104:107], v[148:151], v[188:191], 0
	v_mfma_f32_16x16x32_bf16 v[104:107], v[152:155], v[192:195], v[104:107]
	v_mfma_f32_16x16x32_bf16 v[100:103], v[156:159], v[188:191], 0
	v_mfma_f32_16x16x32_bf16 v[100:103], v[170:173], v[192:195], v[100:103]
	v_mfma_f32_16x16x32_bf16 v[88:91], v[148:151], v[206:209], 0
	v_mfma_f32_16x16x32_bf16 v[88:91], v[152:155], v[210:213], v[88:91]
	v_mfma_f32_16x16x32_bf16 v[84:87], v[156:159], v[206:209], 0
	v_mfma_f32_16x16x32_bf16 v[84:87], v[170:173], v[210:213], v[84:87]
	v_mfma_f32_16x16x32_bf16 v[72:75], v[148:151], v[214:217], 0
	v_mfma_f32_16x16x32_bf16 v[72:75], v[152:155], v[218:221], v[72:75]
	v_mfma_f32_16x16x32_bf16 v[68:71], v[156:159], v[214:217], 0
	v_mfma_f32_16x16x32_bf16 v[68:71], v[170:173], v[218:221], v[68:71]
	s_barrier
	s_setprio 0
	s_add_i32 s24, s43, s38
	v_lshl_add_u64 v[182:183], s[28:29], 0, v[34:35]
	s_mov_b32 m0, s24
	ds_read_b128 v[174:177], v187 offset:16384
	ds_read_b128 v[178:181], v187 offset:17408
	ds_read_b128 v[188:191], v187 offset:18432
	ds_read_b128 v[192:195], v187 offset:19456
	ds_read_b128 v[206:209], v187 offset:20480
	ds_read_b128 v[210:213], v187 offset:21504
	ds_read_b128 v[214:217], v187 offset:22528
	ds_read_b128 v[218:221], v187 offset:23552
	global_load_lds_dwordx4 v[182:183], off
	s_add_i32 m0, s24, 0x2000
	s_add_u32 s24, s28, 0x160000
	v_lshl_add_u64 v[196:197], s[28:29], 0, v[164:165]
	s_addc_u32 s25, s29, 0
	s_add_i32 s43, s60, s38
	global_load_lds_dwordx4 v[196:197], off
	v_lshl_add_u64 v[198:199], s[24:25], 0, v[34:35]
	s_mov_b32 m0, s43
	v_lshl_add_u64 v[200:201], s[30:31], 0, v[162:163]
	global_load_lds_dwordx4 v[198:199], off
	v_lshl_add_u64 v[198:199], s[24:25], 0, v[164:165]
	s_add_i32 m0, s43, 0x2000
	s_nop 0
	global_load_lds_dwordx4 v[198:199], off
	v_lshl_add_u64 v[198:199], s[30:31], 0, v[160:161]
	s_mov_b32 m0, s39
	s_nop 0
	global_load_lds_dwordx4 v[198:199], off
	s_mov_b32 m0, s44
	s_nop 0
	global_load_lds_dwordx4 v[200:201], off
	s_waitcnt vmcnt(8)
	s_waitcnt lgkmcnt(0)
	s_setprio 1
	s_barrier
	v_mfma_f32_16x16x32_bf16 v[64:67], v[132:135], v[174:177], 0
	v_mfma_f32_16x16x32_bf16 v[64:67], v[136:139], v[178:181], v[64:67]
	v_mfma_f32_16x16x32_bf16 v[60:63], v[140:143], v[174:177], 0
	v_mfma_f32_16x16x32_bf16 v[60:63], v[144:147], v[178:181], v[60:63]
	v_mfma_f32_16x16x32_bf16 v[48:51], v[132:135], v[188:191], 0
	v_mfma_f32_16x16x32_bf16 v[48:51], v[136:139], v[192:195], v[48:51]
	v_mfma_f32_16x16x32_bf16 v[44:47], v[140:143], v[188:191], 0
	v_mfma_f32_16x16x32_bf16 v[44:47], v[144:147], v[192:195], v[44:47]
	v_mfma_f32_16x16x32_bf16 v[30:33], v[132:135], v[206:209], 0
	v_mfma_f32_16x16x32_bf16 v[30:33], v[136:139], v[210:213], v[30:33]
	v_mfma_f32_16x16x32_bf16 v[26:29], v[140:143], v[206:209], 0
	v_mfma_f32_16x16x32_bf16 v[26:29], v[144:147], v[210:213], v[26:29]
	v_mfma_f32_16x16x32_bf16 v[14:17], v[132:135], v[214:217], 0
	v_mfma_f32_16x16x32_bf16 v[14:17], v[136:139], v[218:221], v[14:17]
	v_mfma_f32_16x16x32_bf16 v[10:13], v[140:143], v[214:217], 0
	v_mfma_f32_16x16x32_bf16 v[10:13], v[144:147], v[218:221], v[10:13]
	v_mfma_f32_16x16x32_bf16 v[56:59], v[148:151], v[174:177], 0
	v_mfma_f32_16x16x32_bf16 v[56:59], v[152:155], v[178:181], v[56:59]
	v_mfma_f32_16x16x32_bf16 v[52:55], v[156:159], v[174:177], 0
	v_mfma_f32_16x16x32_bf16 v[52:55], v[170:173], v[178:181], v[52:55]
	v_mfma_f32_16x16x32_bf16 v[40:43], v[148:151], v[188:191], 0
	v_mfma_f32_16x16x32_bf16 v[40:43], v[152:155], v[192:195], v[40:43]
	v_mfma_f32_16x16x32_bf16 v[36:39], v[156:159], v[188:191], 0
	v_mfma_f32_16x16x32_bf16 v[36:39], v[170:173], v[192:195], v[36:39]
	v_mfma_f32_16x16x32_bf16 v[22:25], v[148:151], v[206:209], 0
	v_mfma_f32_16x16x32_bf16 v[22:25], v[152:155], v[210:213], v[22:25]
	v_mfma_f32_16x16x32_bf16 v[18:21], v[156:159], v[206:209], 0
	v_mfma_f32_16x16x32_bf16 v[18:21], v[170:173], v[210:213], v[18:21]
	v_mfma_f32_16x16x32_bf16 v[6:9], v[148:151], v[214:217], 0
	v_mfma_f32_16x16x32_bf16 v[6:9], v[152:155], v[218:221], v[6:9]
	v_mfma_f32_16x16x32_bf16 v[2:5], v[156:159], v[214:217], 0
	v_mfma_f32_16x16x32_bf16 v[2:5], v[170:173], v[218:221], v[2:5]
	s_barrier
	s_setprio 0
	s_add_i32 s43, 0, 0x18000
	s_add_i32 s60, 0, 0x1c000
	v_add_u32_e32 v144, s43, v186
	v_add_u32_e32 v170, s60, v186
	ds_read_b128 v[132:135], v144
	ds_read_b128 v[136:139], v144 offset:1024
	ds_read_b128 v[140:143], v144 offset:2048
	ds_read_b128 v[144:147], v144 offset:3072
	ds_read_b128 v[148:151], v170
	ds_read_b128 v[152:155], v170 offset:1024
	ds_read_b128 v[156:159], v170 offset:2048
	ds_read_b128 v[170:173], v170 offset:3072
	s_add_u32 s24, s30, 0x160000
	s_addc_u32 s25, s31, 0
	s_mov_b32 m0, s45
	v_lshl_add_u64 v[222:223], s[24:25], 0, v[160:161]
	ds_read_b128 v[174:177], v187 offset:32768
	ds_read_b128 v[178:181], v187 offset:33792
	ds_read_b128 v[188:191], v187 offset:34816
	ds_read_b128 v[192:195], v187 offset:35840
	ds_read_b128 v[206:209], v187 offset:36864
	ds_read_b128 v[210:213], v187 offset:37888
	ds_read_b128 v[214:217], v187 offset:38912
	ds_read_b128 v[218:221], v187 offset:39936
	global_load_lds_dwordx4 v[222:223], off
	v_lshl_add_u64 v[222:223], s[24:25], 0, v[162:163]
	s_mov_b32 m0, s46
	s_nop 0
	global_load_lds_dwordx4 v[222:223], off
	s_waitcnt vmcnt(8)
	s_waitcnt lgkmcnt(0)
	s_setprio 1
	s_barrier
	v_mfma_f32_16x16x32_bf16 v[128:131], v[132:135], v[174:177], v[128:131]
	v_mfma_f32_16x16x32_bf16 v[128:131], v[136:139], v[178:181], v[128:131]
	v_mfma_f32_16x16x32_bf16 v[124:127], v[140:143], v[174:177], v[124:127]
	v_mfma_f32_16x16x32_bf16 v[124:127], v[144:147], v[178:181], v[124:127]
	v_mfma_f32_16x16x32_bf16 v[112:115], v[132:135], v[188:191], v[112:115]
	v_mfma_f32_16x16x32_bf16 v[112:115], v[136:139], v[192:195], v[112:115]
	v_mfma_f32_16x16x32_bf16 v[108:111], v[140:143], v[188:191], v[108:111]
	v_mfma_f32_16x16x32_bf16 v[108:111], v[144:147], v[192:195], v[108:111]
	v_mfma_f32_16x16x32_bf16 v[96:99], v[132:135], v[206:209], v[96:99]
	v_mfma_f32_16x16x32_bf16 v[96:99], v[136:139], v[210:213], v[96:99]
	v_mfma_f32_16x16x32_bf16 v[92:95], v[140:143], v[206:209], v[92:95]
	v_mfma_f32_16x16x32_bf16 v[92:95], v[144:147], v[210:213], v[92:95]
	v_mfma_f32_16x16x32_bf16 v[80:83], v[132:135], v[214:217], v[80:83]
	v_mfma_f32_16x16x32_bf16 v[80:83], v[136:139], v[218:221], v[80:83]
	v_mfma_f32_16x16x32_bf16 v[76:79], v[140:143], v[214:217], v[76:79]
	v_mfma_f32_16x16x32_bf16 v[76:79], v[144:147], v[218:221], v[76:79]
	v_mfma_f32_16x16x32_bf16 v[120:123], v[148:151], v[174:177], v[120:123]
	v_mfma_f32_16x16x32_bf16 v[120:123], v[152:155], v[178:181], v[120:123]
	v_mfma_f32_16x16x32_bf16 v[116:119], v[156:159], v[174:177], v[116:119]
	v_mfma_f32_16x16x32_bf16 v[116:119], v[170:173], v[178:181], v[116:119]
	v_mfma_f32_16x16x32_bf16 v[104:107], v[148:151], v[188:191], v[104:107]
	v_mfma_f32_16x16x32_bf16 v[104:107], v[152:155], v[192:195], v[104:107]
	v_mfma_f32_16x16x32_bf16 v[100:103], v[156:159], v[188:191], v[100:103]
	v_mfma_f32_16x16x32_bf16 v[100:103], v[170:173], v[192:195], v[100:103]
	v_mfma_f32_16x16x32_bf16 v[88:91], v[148:151], v[206:209], v[88:91]
	v_mfma_f32_16x16x32_bf16 v[88:91], v[152:155], v[210:213], v[88:91]
	v_mfma_f32_16x16x32_bf16 v[84:87], v[156:159], v[206:209], v[84:87]
	v_mfma_f32_16x16x32_bf16 v[84:87], v[170:173], v[210:213], v[84:87]
	v_mfma_f32_16x16x32_bf16 v[72:75], v[148:151], v[214:217], v[72:75]
	v_mfma_f32_16x16x32_bf16 v[72:75], v[152:155], v[218:221], v[72:75]
	v_mfma_f32_16x16x32_bf16 v[68:71], v[156:159], v[214:217], v[68:71]
	v_mfma_f32_16x16x32_bf16 v[68:71], v[170:173], v[218:221], v[68:71]
	s_barrier
	s_setprio 0
	s_add_i32 s24, s43, s38
	v_lshl_add_u64 v[182:183], v[182:183], 0, s[18:19]
	s_mov_b32 m0, s24
	ds_read_b128 v[174:177], v187 offset:49152
	ds_read_b128 v[178:181], v187 offset:50176
	ds_read_b128 v[188:191], v187 offset:51200
	ds_read_b128 v[192:195], v187 offset:52224
	ds_read_b128 v[206:209], v187 offset:53248
	ds_read_b128 v[210:213], v187 offset:54272
	ds_read_b128 v[214:217], v187 offset:55296
	ds_read_b128 v[218:221], v187 offset:56320
	global_load_lds_dwordx4 v[182:183], off
	s_add_i32 m0, s24, 0x2000
	s_add_u32 s24, s28, 0x160080
	v_lshl_add_u64 v[182:183], v[196:197], 0, s[18:19]
	s_addc_u32 s25, s29, 0
	s_add_i32 s28, s60, s38
	global_load_lds_dwordx4 v[182:183], off
	v_lshl_add_u64 v[182:183], s[24:25], 0, v[34:35]
	s_mov_b32 m0, s28
	s_nop 0
	global_load_lds_dwordx4 v[182:183], off
	v_lshl_add_u64 v[182:183], s[24:25], 0, v[164:165]
	s_add_i32 m0, s28, 0x2000
	s_nop 0
	global_load_lds_dwordx4 v[182:183], off
	v_lshl_add_u64 v[182:183], v[198:199], 0, s[18:19]
	s_mov_b32 m0, s47
	s_nop 0
	global_load_lds_dwordx4 v[182:183], off
	v_lshl_add_u64 v[182:183], v[200:201], 0, s[18:19]
	s_mov_b32 m0, s52
	s_nop 0
	global_load_lds_dwordx4 v[182:183], off
	s_waitcnt vmcnt(8)
	s_waitcnt lgkmcnt(0)
	s_setprio 1
	s_barrier
	v_mfma_f32_16x16x32_bf16 v[64:67], v[132:135], v[174:177], v[64:67]
	v_mfma_f32_16x16x32_bf16 v[64:67], v[136:139], v[178:181], v[64:67]
	v_mfma_f32_16x16x32_bf16 v[60:63], v[140:143], v[174:177], v[60:63]
	v_mfma_f32_16x16x32_bf16 v[60:63], v[144:147], v[178:181], v[60:63]
	v_mfma_f32_16x16x32_bf16 v[48:51], v[132:135], v[188:191], v[48:51]
	v_mfma_f32_16x16x32_bf16 v[48:51], v[136:139], v[192:195], v[48:51]
	v_mfma_f32_16x16x32_bf16 v[44:47], v[140:143], v[188:191], v[44:47]
	v_mfma_f32_16x16x32_bf16 v[44:47], v[144:147], v[192:195], v[44:47]
	v_mfma_f32_16x16x32_bf16 v[30:33], v[132:135], v[206:209], v[30:33]
	v_mfma_f32_16x16x32_bf16 v[30:33], v[136:139], v[210:213], v[30:33]
	v_mfma_f32_16x16x32_bf16 v[26:29], v[140:143], v[206:209], v[26:29]
	v_mfma_f32_16x16x32_bf16 v[26:29], v[144:147], v[210:213], v[26:29]
	v_mfma_f32_16x16x32_bf16 v[14:17], v[132:135], v[214:217], v[14:17]
	v_mfma_f32_16x16x32_bf16 v[14:17], v[136:139], v[218:221], v[14:17]
	v_mfma_f32_16x16x32_bf16 v[10:13], v[140:143], v[214:217], v[10:13]
	v_mfma_f32_16x16x32_bf16 v[10:13], v[144:147], v[218:221], v[10:13]
	v_mfma_f32_16x16x32_bf16 v[56:59], v[148:151], v[174:177], v[56:59]
	v_mfma_f32_16x16x32_bf16 v[56:59], v[152:155], v[178:181], v[56:59]
	v_mfma_f32_16x16x32_bf16 v[52:55], v[156:159], v[174:177], v[52:55]
	v_mfma_f32_16x16x32_bf16 v[52:55], v[170:173], v[178:181], v[52:55]
	v_mfma_f32_16x16x32_bf16 v[40:43], v[148:151], v[188:191], v[40:43]
	v_mfma_f32_16x16x32_bf16 v[40:43], v[152:155], v[192:195], v[40:43]
	v_mfma_f32_16x16x32_bf16 v[36:39], v[156:159], v[188:191], v[36:39]
	v_mfma_f32_16x16x32_bf16 v[36:39], v[170:173], v[192:195], v[36:39]
	v_mfma_f32_16x16x32_bf16 v[22:25], v[148:151], v[206:209], v[22:25]
	v_mfma_f32_16x16x32_bf16 v[22:25], v[152:155], v[210:213], v[22:25]
	v_mfma_f32_16x16x32_bf16 v[18:21], v[156:159], v[206:209], v[18:21]
	v_mfma_f32_16x16x32_bf16 v[18:21], v[170:173], v[210:213], v[18:21]
	v_mfma_f32_16x16x32_bf16 v[6:9], v[148:151], v[214:217], v[6:9]
	v_mfma_f32_16x16x32_bf16 v[6:9], v[152:155], v[218:221], v[6:9]
	v_mfma_f32_16x16x32_bf16 v[2:5], v[156:159], v[214:217], v[2:5]
	v_mfma_f32_16x16x32_bf16 v[2:5], v[170:173], v[218:221], v[2:5]
	s_barrier
	s_setprio 0
	s_add_i32 s42, s42, 2
	s_add_u32 s11, s11, 0x100
	s_addc_u32 s13, s13, 0
	s_cmpk_gt_u32 s42, 0x55
	s_mov_b64 s[24:25], s[26:27]
	s_cbranch_scc0 .LBB0_546

.LBB0_806:
	s_ashr_i32 s21, s20, 31
	s_lshl_b64 s[22:23], s[20:21], 20
	s_add_u32 s22, s38, s22
	s_addc_u32 s23, s39, s23
	s_and_b64 s[24:25], s[40:41], exec
	s_cselect_b32 s21, s23, s31
	s_cselect_b32 s27, s22, s30
	s_ashr_i32 s17, s16, 31
	s_lshl_b64 s[24:25], s[16:17], 20
	s_add_u32 s24, s44, s24
	s_addc_u32 s25, s45, s25
	s_and_b64 s[36:37], s[40:41], exec
	s_cselect_b32 s17, s25, s35
	s_cselect_b32 s66, s24, s34
	s_ashr_i32 s29, s28, 31
	s_lshl_b64 s[36:37], s[28:29], 13
	v_lshl_add_u64 v[220:221], v[214:215], 0, s[36:37]
	s_add_u32 s36, s30, 0x80080
	s_addc_u32 s37, s31, 0
	s_add_u32 s29, s34, 0x100
	v_lshl_add_u64 v[222:223], s[36:37], 0, v[216:217]
	v_lshl_add_u64 v[224:225], s[36:37], 0, v[218:219]
	s_addc_u32 s67, s35, 0
	s_mov_b32 s68, -2
	s_mov_b64 s[34:35], 0
	s_branch .LPW_808

.LPW_807:
	v_mfma_f32_16x16x32_bf16 v[128:131], v[148:151], v[188:191], 0
	v_mfma_f32_16x16x32_bf16 v[128:131], v[152:155], v[192:195], v[128:131]
	v_mfma_f32_16x16x32_bf16 v[124:127], v[156:159], v[188:191], 0
	v_mfma_f32_16x16x32_bf16 v[124:127], v[160:163], v[192:195], v[124:127]
	v_mfma_f32_16x16x32_bf16 v[112:115], v[148:151], v[180:183], 0
	v_mfma_f32_16x16x32_bf16 v[112:115], v[152:155], v[184:187], v[112:115]
	v_mfma_f32_16x16x32_bf16 v[108:111], v[156:159], v[180:183], 0
	v_mfma_f32_16x16x32_bf16 v[108:111], v[160:163], v[184:187], v[108:111]
	v_mfma_f32_16x16x32_bf16 v[96:99], v[148:151], v[172:175], 0
	v_mfma_f32_16x16x32_bf16 v[96:99], v[152:155], v[176:179], v[96:99]
	v_mfma_f32_16x16x32_bf16 v[92:95], v[156:159], v[172:175], 0
	v_mfma_f32_16x16x32_bf16 v[92:95], v[160:163], v[176:179], v[92:95]
	v_mfma_f32_16x16x32_bf16 v[80:83], v[148:151], v[164:167], 0
	v_mfma_f32_16x16x32_bf16 v[80:83], v[152:155], v[168:171], v[80:83]
	v_mfma_f32_16x16x32_bf16 v[76:79], v[156:159], v[164:167], 0
	v_mfma_f32_16x16x32_bf16 v[76:79], v[160:163], v[168:171], v[76:79]
	v_mfma_f32_16x16x32_bf16 v[120:123], v[132:135], v[188:191], 0
	v_mfma_f32_16x16x32_bf16 v[120:123], v[136:139], v[192:195], v[120:123]
	v_mfma_f32_16x16x32_bf16 v[116:119], v[140:143], v[188:191], 0
	v_mfma_f32_16x16x32_bf16 v[116:119], v[144:147], v[192:195], v[116:119]
	v_mfma_f32_16x16x32_bf16 v[104:107], v[132:135], v[180:183], 0
	v_mfma_f32_16x16x32_bf16 v[104:107], v[136:139], v[184:187], v[104:107]
	v_mfma_f32_16x16x32_bf16 v[100:103], v[140:143], v[180:183], 0
	v_mfma_f32_16x16x32_bf16 v[100:103], v[144:147], v[184:187], v[100:103]
	v_mfma_f32_16x16x32_bf16 v[88:91], v[132:135], v[172:175], 0
	v_mfma_f32_16x16x32_bf16 v[88:91], v[136:139], v[176:179], v[88:91]
	v_mfma_f32_16x16x32_bf16 v[84:87], v[140:143], v[172:175], 0
	v_mfma_f32_16x16x32_bf16 v[84:87], v[144:147], v[176:179], v[84:87]
	v_mfma_f32_16x16x32_bf16 v[72:75], v[132:135], v[164:167], 0
	v_mfma_f32_16x16x32_bf16 v[72:75], v[136:139], v[168:171], v[72:75]
	v_mfma_f32_16x16x32_bf16 v[68:71], v[140:143], v[164:167], 0
	v_mfma_f32_16x16x32_bf16 v[68:71], v[144:147], v[168:171], v[68:71]
	s_barrier
	s_setprio 0
	s_mov_b32 m0, s52
	v_lshl_add_u64 v[198:199], s[36:37], 0, v[208:209]
	s_add_u32 s70, s36, 0x80000
	ds_read_b128 v[164:167], v240 offset:16384
	ds_read_b128 v[168:171], v240 offset:17408
	ds_read_b128 v[172:175], v240 offset:18432
	ds_read_b128 v[176:179], v240 offset:19456
	ds_read_b128 v[180:183], v240 offset:20480
	ds_read_b128 v[184:187], v240 offset:21504
	ds_read_b128 v[188:191], v240 offset:22528
	ds_read_b128 v[192:195], v240 offset:23552
	global_load_lds_dwordx4 v[198:199], off
	v_lshl_add_u64 v[200:201], s[36:37], 0, v[212:213]
	s_mov_b32 m0, s54
	s_addc_u32 s71, s37, 0
	global_load_lds_dwordx4 v[200:201], off
	v_lshl_add_u64 v[242:243], s[70:71], 0, v[208:209]
	s_mov_b32 m0, s55
	v_lshl_add_u64 v[244:245], s[42:43], 0, v[210:211]
	global_load_lds_dwordx4 v[242:243], off
	v_lshl_add_u64 v[242:243], s[70:71], 0, v[212:213]
	s_mov_b32 m0, s59
	s_nop 0
	global_load_lds_dwordx4 v[242:243], off
	v_lshl_add_u64 v[242:243], s[42:43], 0, v[206:207]
	s_mov_b32 m0, s47
	s_nop 0
	global_load_lds_dwordx4 v[242:243], off
	s_mov_b32 m0, s60
	s_nop 0
	global_load_lds_dwordx4 v[244:245], off
	s_waitcnt vmcnt(8)
	s_waitcnt lgkmcnt(0)
	s_setprio 1
	s_barrier
	v_mfma_f32_16x16x32_bf16 v[64:67], v[148:151], v[164:167], 0
	v_mfma_f32_16x16x32_bf16 v[64:67], v[152:155], v[168:171], v[64:67]
	v_mfma_f32_16x16x32_bf16 v[60:63], v[156:159], v[164:167], 0
	v_mfma_f32_16x16x32_bf16 v[60:63], v[160:163], v[168:171], v[60:63]
	v_mfma_f32_16x16x32_bf16 v[48:51], v[148:151], v[172:175], 0
	v_mfma_f32_16x16x32_bf16 v[48:51], v[152:155], v[176:179], v[48:51]
	v_mfma_f32_16x16x32_bf16 v[44:47], v[156:159], v[172:175], 0
	v_mfma_f32_16x16x32_bf16 v[44:47], v[160:163], v[176:179], v[44:47]
	v_mfma_f32_16x16x32_bf16 v[30:33], v[148:151], v[180:183], 0
	v_mfma_f32_16x16x32_bf16 v[30:33], v[152:155], v[184:187], v[30:33]
	v_mfma_f32_16x16x32_bf16 v[26:29], v[156:159], v[180:183], 0
	v_mfma_f32_16x16x32_bf16 v[26:29], v[160:163], v[184:187], v[26:29]
	v_mfma_f32_16x16x32_bf16 v[14:17], v[148:151], v[188:191], 0
	v_mfma_f32_16x16x32_bf16 v[14:17], v[152:155], v[192:195], v[14:17]
	v_mfma_f32_16x16x32_bf16 v[10:13], v[156:159], v[188:191], 0
	v_mfma_f32_16x16x32_bf16 v[10:13], v[160:163], v[192:195], v[10:13]
	v_mfma_f32_16x16x32_bf16 v[56:59], v[132:135], v[164:167], 0
	v_mfma_f32_16x16x32_bf16 v[56:59], v[136:139], v[168:171], v[56:59]
	v_mfma_f32_16x16x32_bf16 v[52:55], v[140:143], v[164:167], 0
	v_mfma_f32_16x16x32_bf16 v[52:55], v[144:147], v[168:171], v[52:55]
	v_mfma_f32_16x16x32_bf16 v[40:43], v[132:135], v[172:175], 0
	v_mfma_f32_16x16x32_bf16 v[40:43], v[136:139], v[176:179], v[40:43]
	v_mfma_f32_16x16x32_bf16 v[36:39], v[140:143], v[172:175], 0
	v_mfma_f32_16x16x32_bf16 v[36:39], v[144:147], v[176:179], v[36:39]
	v_mfma_f32_16x16x32_bf16 v[22:25], v[132:135], v[180:183], 0
	v_mfma_f32_16x16x32_bf16 v[22:25], v[136:139], v[184:187], v[22:25]
	v_mfma_f32_16x16x32_bf16 v[18:21], v[140:143], v[180:183], 0
	v_mfma_f32_16x16x32_bf16 v[18:21], v[144:147], v[184:187], v[18:21]
	v_mfma_f32_16x16x32_bf16 v[6:9], v[132:135], v[188:191], 0
	v_mfma_f32_16x16x32_bf16 v[6:9], v[136:139], v[192:195], v[6:9]
	v_mfma_f32_16x16x32_bf16 v[2:5], v[140:143], v[188:191], 0
	v_mfma_f32_16x16x32_bf16 v[2:5], v[144:147], v[192:195], v[2:5]
	s_barrier
	s_setprio 0
	s_add_i32 s69, 0, 0x18000
	v_add_u32_e32 v34, s69, v227
	s_add_i32 s70, 0, 0x1c000
	ds_read_b128 v[132:135], v34
	ds_read_b128 v[136:139], v34 offset:1024
	ds_read_b128 v[140:143], v34 offset:2048
	ds_read_b128 v[144:147], v34 offset:3072
	v_add_u32_e32 v34, s70, v227
	ds_read_b128 v[148:151], v34
	ds_read_b128 v[152:155], v34 offset:1024
	ds_read_b128 v[156:159], v34 offset:2048
	ds_read_b128 v[160:163], v34 offset:3072
	s_add_u32 s42, s42, 0x80000
	s_addc_u32 s43, s43, 0
	s_mov_b32 m0, s61
	v_lshl_add_u64 v[246:247], s[42:43], 0, v[206:207]
	ds_read_b128 v[164:167], v240 offset:32768
	ds_read_b128 v[168:171], v240 offset:33792
	ds_read_b128 v[172:175], v240 offset:34816
	ds_read_b128 v[176:179], v240 offset:35840
	ds_read_b128 v[180:183], v240 offset:36864
	ds_read_b128 v[184:187], v240 offset:37888
	ds_read_b128 v[188:191], v240 offset:38912
	ds_read_b128 v[192:195], v240 offset:39936
	global_load_lds_dwordx4 v[246:247], off
	v_lshl_add_u64 v[246:247], s[42:43], 0, v[210:211]
	s_mov_b32 m0, s62
	s_nop 0
	global_load_lds_dwordx4 v[246:247], off
	s_waitcnt vmcnt(8)
	s_waitcnt lgkmcnt(0)
	s_setprio 1
	s_barrier
	v_mfma_f32_16x16x32_bf16 v[128:131], v[132:135], v[164:167], v[128:131]
	v_mfma_f32_16x16x32_bf16 v[128:131], v[136:139], v[168:171], v[128:131]
	v_mfma_f32_16x16x32_bf16 v[124:127], v[140:143], v[164:167], v[124:127]
	v_mfma_f32_16x16x32_bf16 v[124:127], v[144:147], v[168:171], v[124:127]
	v_mfma_f32_16x16x32_bf16 v[112:115], v[132:135], v[172:175], v[112:115]
	v_mfma_f32_16x16x32_bf16 v[112:115], v[136:139], v[176:179], v[112:115]
	v_mfma_f32_16x16x32_bf16 v[108:111], v[140:143], v[172:175], v[108:111]
	v_mfma_f32_16x16x32_bf16 v[108:111], v[144:147], v[176:179], v[108:111]
	v_mfma_f32_16x16x32_bf16 v[96:99], v[132:135], v[180:183], v[96:99]
	v_mfma_f32_16x16x32_bf16 v[96:99], v[136:139], v[184:187], v[96:99]
	v_mfma_f32_16x16x32_bf16 v[92:95], v[140:143], v[180:183], v[92:95]
	v_mfma_f32_16x16x32_bf16 v[92:95], v[144:147], v[184:187], v[92:95]
	v_mfma_f32_16x16x32_bf16 v[80:83], v[132:135], v[188:191], v[80:83]
	v_mfma_f32_16x16x32_bf16 v[80:83], v[136:139], v[192:195], v[80:83]
	v_mfma_f32_16x16x32_bf16 v[76:79], v[140:143], v[188:191], v[76:79]
	v_mfma_f32_16x16x32_bf16 v[76:79], v[144:147], v[192:195], v[76:79]
	v_mfma_f32_16x16x32_bf16 v[120:123], v[148:151], v[164:167], v[120:123]
	v_mfma_f32_16x16x32_bf16 v[120:123], v[152:155], v[168:171], v[120:123]
	v_mfma_f32_16x16x32_bf16 v[116:119], v[156:159], v[164:167], v[116:119]
	v_mfma_f32_16x16x32_bf16 v[116:119], v[160:163], v[168:171], v[116:119]
	v_mfma_f32_16x16x32_bf16 v[104:107], v[148:151], v[172:175], v[104:107]
	v_mfma_f32_16x16x32_bf16 v[104:107], v[152:155], v[176:179], v[104:107]
	v_mfma_f32_16x16x32_bf16 v[100:103], v[156:159], v[172:175], v[100:103]
	v_mfma_f32_16x16x32_bf16 v[100:103], v[160:163], v[176:179], v[100:103]
	v_mfma_f32_16x16x32_bf16 v[88:91], v[148:151], v[180:183], v[88:91]
	v_mfma_f32_16x16x32_bf16 v[88:91], v[152:155], v[184:187], v[88:91]
	v_mfma_f32_16x16x32_bf16 v[84:87], v[156:159], v[180:183], v[84:87]
	v_mfma_f32_16x16x32_bf16 v[84:87], v[160:163], v[184:187], v[84:87]
	v_mfma_f32_16x16x32_bf16 v[72:75], v[148:151], v[188:191], v[72:75]
	v_mfma_f32_16x16x32_bf16 v[72:75], v[152:155], v[192:195], v[72:75]
	v_mfma_f32_16x16x32_bf16 v[68:71], v[156:159], v[188:191], v[68:71]
	v_mfma_f32_16x16x32_bf16 v[68:71], v[160:163], v[192:195], v[68:71]
	s_barrier
	s_setprio 0
	s_add_i32 s42, s69, s46
	v_lshl_add_u64 v[198:199], v[198:199], 0, s[18:19]
	s_mov_b32 m0, s42
	ds_read_b128 v[164:167], v240 offset:49152
	ds_read_b128 v[168:171], v240 offset:50176
	ds_read_b128 v[172:175], v240 offset:51200
	ds_read_b128 v[176:179], v240 offset:52224
	ds_read_b128 v[180:183], v240 offset:53248
	ds_read_b128 v[184:187], v240 offset:54272
	ds_read_b128 v[188:191], v240 offset:55296
	ds_read_b128 v[192:195], v240 offset:56320
	global_load_lds_dwordx4 v[198:199], off
	s_add_i32 m0, s42, 0x2000
	s_add_u32 s36, s36, 0x80080
	v_lshl_add_u64 v[198:199], v[200:201], 0, s[18:19]
	s_addc_u32 s37, s37, 0
	s_add_i32 s42, s70, s46
	global_load_lds_dwordx4 v[198:199], off
	v_lshl_add_u64 v[198:199], s[36:37], 0, v[208:209]
	s_mov_b32 m0, s42
	s_nop 0
	global_load_lds_dwordx4 v[198:199], off
	v_lshl_add_u64 v[198:199], s[36:37], 0, v[212:213]
	s_add_i32 m0, s42, 0x2000
	s_nop 0
	global_load_lds_dwordx4 v[198:199], off
	v_lshl_add_u64 v[198:199], v[242:243], 0, s[18:19]
	s_mov_b32 m0, s63
	s_nop 0
	global_load_lds_dwordx4 v[198:199], off
	v_lshl_add_u64 v[198:199], v[244:245], 0, s[18:19]
	s_mov_b32 m0, s64
	s_nop 0
	global_load_lds_dwordx4 v[198:199], off
	s_waitcnt vmcnt(8)
	s_waitcnt lgkmcnt(0)
	s_setprio 1
	s_barrier
	v_mfma_f32_16x16x32_bf16 v[64:67], v[132:135], v[164:167], v[64:67]
	v_mfma_f32_16x16x32_bf16 v[64:67], v[136:139], v[168:171], v[64:67]
	v_mfma_f32_16x16x32_bf16 v[60:63], v[140:143], v[164:167], v[60:63]
	v_mfma_f32_16x16x32_bf16 v[60:63], v[144:147], v[168:171], v[60:63]
	v_mfma_f32_16x16x32_bf16 v[48:51], v[132:135], v[172:175], v[48:51]
	v_mfma_f32_16x16x32_bf16 v[48:51], v[136:139], v[176:179], v[48:51]
	v_mfma_f32_16x16x32_bf16 v[44:47], v[140:143], v[172:175], v[44:47]
	v_mfma_f32_16x16x32_bf16 v[44:47], v[144:147], v[176:179], v[44:47]
	v_mfma_f32_16x16x32_bf16 v[30:33], v[132:135], v[180:183], v[30:33]
	v_mfma_f32_16x16x32_bf16 v[30:33], v[136:139], v[184:187], v[30:33]
	v_mfma_f32_16x16x32_bf16 v[26:29], v[140:143], v[180:183], v[26:29]
	v_mfma_f32_16x16x32_bf16 v[26:29], v[144:147], v[184:187], v[26:29]
	v_mfma_f32_16x16x32_bf16 v[14:17], v[132:135], v[188:191], v[14:17]
	v_mfma_f32_16x16x32_bf16 v[14:17], v[136:139], v[192:195], v[14:17]
	v_mfma_f32_16x16x32_bf16 v[10:13], v[140:143], v[188:191], v[10:13]
	v_mfma_f32_16x16x32_bf16 v[10:13], v[144:147], v[192:195], v[10:13]
	v_mfma_f32_16x16x32_bf16 v[56:59], v[148:151], v[164:167], v[56:59]
	v_mfma_f32_16x16x32_bf16 v[56:59], v[152:155], v[168:171], v[56:59]
	v_mfma_f32_16x16x32_bf16 v[52:55], v[156:159], v[164:167], v[52:55]
	v_mfma_f32_16x16x32_bf16 v[52:55], v[160:163], v[168:171], v[52:55]
	v_mfma_f32_16x16x32_bf16 v[40:43], v[148:151], v[172:175], v[40:43]
	v_mfma_f32_16x16x32_bf16 v[40:43], v[152:155], v[176:179], v[40:43]
	v_mfma_f32_16x16x32_bf16 v[36:39], v[156:159], v[172:175], v[36:39]
	v_mfma_f32_16x16x32_bf16 v[36:39], v[160:163], v[176:179], v[36:39]
	v_mfma_f32_16x16x32_bf16 v[22:25], v[148:151], v[180:183], v[22:25]
	v_mfma_f32_16x16x32_bf16 v[22:25], v[152:155], v[184:187], v[22:25]
	v_mfma_f32_16x16x32_bf16 v[18:21], v[156:159], v[180:183], v[18:21]
	v_mfma_f32_16x16x32_bf16 v[18:21], v[160:163], v[184:187], v[18:21]
	v_mfma_f32_16x16x32_bf16 v[6:9], v[148:151], v[188:191], v[6:9]
	v_mfma_f32_16x16x32_bf16 v[6:9], v[152:155], v[192:195], v[6:9]
	v_mfma_f32_16x16x32_bf16 v[2:5], v[156:159], v[188:191], v[2:5]
	v_mfma_f32_16x16x32_bf16 v[2:5], v[160:163], v[192:195], v[2:5]
	s_barrier
	s_setprio 0
	s_add_i32 s68, s68, 2
	s_add_u32 s34, s34, 0x100
	s_addc_u32 s35, s35, 0
	s_cmp_gt_u32 s68, 29
	s_cbranch_scc0 .LBB0_808
	s_branch .LBB0_810
.LPW_win:
	s_add_i32 m0, s47, 0x21200
	s_nop 0
	global_load_lds_dwordx4 v[220:221], off
	s_branch .LPW_807
.LBB0_808:
	v_add_u32_e32 v34, 0, v227
	v_add_u32_e32 v132, 0x10000, v34
	v_add_u32_e32 v34, 0x14000, v34
	ds_read_b128 v[148:151], v132
	ds_read_b128 v[152:155], v132 offset:1024
	ds_read_b128 v[156:159], v132 offset:2048
	ds_read_b128 v[160:163], v132 offset:3072
	ds_read_b128 v[132:135], v34
	ds_read_b128 v[136:139], v34 offset:1024
	ds_read_b128 v[140:143], v34 offset:2048
	ds_read_b128 v[144:147], v34 offset:3072
	v_lshl_add_u64 v[198:199], v[222:223], 0, s[34:35]
	s_add_i32 m0, s47, 0xc000
	ds_read_b128 v[188:191], v240
	ds_read_b128 v[192:195], v240 offset:1024
	ds_read_b128 v[180:183], v240 offset:2048
	ds_read_b128 v[184:187], v240 offset:3072
	ds_read_b128 v[172:175], v240 offset:4096
	ds_read_b128 v[176:179], v240 offset:5120
	ds_read_b128 v[164:167], v240 offset:6144
	ds_read_b128 v[168:171], v240 offset:7168
	global_load_lds_dwordx4 v[198:199], off
	v_lshl_add_u64 v[198:199], v[224:225], 0, s[34:35]
	s_add_i32 m0, s47, 0xe000
	s_cmp_lg_u32 s34, 0
	global_load_lds_dwordx4 v[198:199], off
	s_waitcnt vmcnt(8)
	s_waitcnt lgkmcnt(0)
	s_add_u32 s36, s30, s34
	s_addc_u32 s37, s31, s35
	s_add_u32 s36, s36, 0x100
	s_addc_u32 s37, s37, 0
	s_add_u32 s69, s29, s34
	s_addc_u32 s70, s67, s35
	s_cmpk_eq_i32 s34, 0xf00
	s_cselect_b32 s43, s21, s37
	s_cselect_b32 s42, s27, s36
	s_cselect_b32 s37, s17, s70
	s_cselect_b32 s36, s66, s69
	s_cmp_lg_u32 s34, 0
	s_setprio 1
	s_barrier
	s_cbranch_scc0 .Lrss_win

.LBB0_1642:
	s_ashr_i32 s23, s22, 31
	s_lshl_b64 s[24:25], s[22:23], 20
	s_add_u32 s24, s44, s24
	s_addc_u32 s25, s45, s25
	s_and_b64 s[26:27], s[38:39], exec
	s_cselect_b32 s13, s25, s35
	s_cselect_b32 s23, s24, s34
	s_ashr_i32 s21, s20, 31
	s_lshl_b64 s[26:27], s[20:21], 20
	s_add_u32 s26, s46, s26
	s_addc_u32 s27, s47, s27
	s_and_b64 s[28:29], s[38:39], exec
	s_cselect_b32 s21, s27, s37
	s_cselect_b32 s76, s26, s36
	s_ashr_i32 s31, s30, 31
	s_lshl_b64 s[28:29], s[30:31], 13
	s_add_u32 s40, s34, 0x80080
	s_addc_u32 s41, s35, 0
	v_mov_b32_e32 v34, v35
	v_mov_b32_e32 v36, v35
	v_mov_b32_e32 v37, v35
	s_add_u32 s31, s36, 0x100
	v_lshl_add_u64 v[222:223], v[216:217], 0, s[28:29]
	v_lshl_add_u64 v[224:225], s[40:41], 0, v[218:219]
	v_lshl_add_u64 v[226:227], s[40:41], 0, v[220:221]
	s_addc_u32 s77, s37, 0
	s_mov_b32 vcc_lo, -2
	s_mov_b64 s[36:37], 0
	s_branch .LPO_1644

.LPO_1643:
	v_mfma_f32_16x16x32_bf16 v[130:133], v[150:153], v[190:193], 0
	v_mfma_f32_16x16x32_bf16 v[130:133], v[154:157], v[194:197], v[130:133]
	v_mfma_f32_16x16x32_bf16 v[126:129], v[158:161], v[190:193], 0
	v_mfma_f32_16x16x32_bf16 v[126:129], v[162:165], v[194:197], v[126:129]
	v_mfma_f32_16x16x32_bf16 v[114:117], v[150:153], v[182:185], 0
	v_mfma_f32_16x16x32_bf16 v[114:117], v[154:157], v[186:189], v[114:117]
	v_mfma_f32_16x16x32_bf16 v[110:113], v[158:161], v[182:185], 0
	v_mfma_f32_16x16x32_bf16 v[110:113], v[162:165], v[186:189], v[110:113]
	v_mfma_f32_16x16x32_bf16 v[98:101], v[150:153], v[174:177], 0
	v_mfma_f32_16x16x32_bf16 v[98:101], v[154:157], v[178:181], v[98:101]
	v_mfma_f32_16x16x32_bf16 v[94:97], v[158:161], v[174:177], 0
	v_mfma_f32_16x16x32_bf16 v[94:97], v[162:165], v[178:181], v[94:97]
	v_mfma_f32_16x16x32_bf16 v[82:85], v[150:153], v[166:169], 0
	v_mfma_f32_16x16x32_bf16 v[82:85], v[154:157], v[170:173], v[82:85]
	v_mfma_f32_16x16x32_bf16 v[78:81], v[158:161], v[166:169], 0
	v_mfma_f32_16x16x32_bf16 v[78:81], v[162:165], v[170:173], v[78:81]
	v_mfma_f32_16x16x32_bf16 v[122:125], v[134:137], v[190:193], 0
	v_mfma_f32_16x16x32_bf16 v[122:125], v[138:141], v[194:197], v[122:125]
	v_mfma_f32_16x16x32_bf16 v[118:121], v[142:145], v[190:193], 0
	v_mfma_f32_16x16x32_bf16 v[118:121], v[146:149], v[194:197], v[118:121]
	v_mfma_f32_16x16x32_bf16 v[106:109], v[134:137], v[182:185], 0
	v_mfma_f32_16x16x32_bf16 v[106:109], v[138:141], v[186:189], v[106:109]
	v_mfma_f32_16x16x32_bf16 v[102:105], v[142:145], v[182:185], 0
	v_mfma_f32_16x16x32_bf16 v[102:105], v[146:149], v[186:189], v[102:105]
	v_mfma_f32_16x16x32_bf16 v[90:93], v[134:137], v[174:177], 0
	v_mfma_f32_16x16x32_bf16 v[90:93], v[138:141], v[178:181], v[90:93]
	v_mfma_f32_16x16x32_bf16 v[86:89], v[142:145], v[174:177], 0
	v_mfma_f32_16x16x32_bf16 v[86:89], v[146:149], v[178:181], v[86:89]
	v_mfma_f32_16x16x32_bf16 v[74:77], v[134:137], v[166:169], 0
	v_mfma_f32_16x16x32_bf16 v[74:77], v[138:141], v[170:173], v[74:77]
	v_mfma_f32_16x16x32_bf16 v[70:73], v[142:145], v[166:169], 0
	v_mfma_f32_16x16x32_bf16 v[70:73], v[146:149], v[170:173], v[70:73]
	s_barrier
	s_setprio 0
	s_mov_b32 m0, s55
	v_lshl_add_u64 v[198:199], s[40:41], 0, v[210:211]
	s_add_u32 s78, s40, 0x80000
	ds_read_b128 v[166:169], v244 offset:16384
	ds_read_b128 v[170:173], v244 offset:17408
	ds_read_b128 v[174:177], v244 offset:18432
	ds_read_b128 v[178:181], v244 offset:19456
	ds_read_b128 v[182:185], v244 offset:20480
	ds_read_b128 v[186:189], v244 offset:21504
	ds_read_b128 v[190:193], v244 offset:22528
	ds_read_b128 v[194:197], v244 offset:23552
	global_load_lds_dwordx4 v[198:199], off
	v_lshl_add_u64 v[200:201], s[40:41], 0, v[214:215]
	s_mov_b32 m0, s59
	s_addc_u32 s79, s41, 0
	global_load_lds_dwordx4 v[200:201], off
	v_lshl_add_u64 v[36:37], s[78:79], 0, v[210:211]
	s_mov_b32 m0, s60
	v_lshl_add_u64 v[246:247], s[42:43], 0, v[208:209]
	global_load_lds_dwordx4 v[36:37], off
	v_lshl_add_u64 v[36:37], s[78:79], 0, v[214:215]
	s_mov_b32 m0, s61
	v_lshl_add_u64 v[248:249], s[42:43], 0, v[212:213]
	global_load_lds_dwordx4 v[36:37], off
	s_mov_b32 m0, s54
	s_nop 0
	global_load_lds_dwordx4 v[246:247], off
	s_mov_b32 m0, s62
	s_nop 0
	global_load_lds_dwordx4 v[248:249], off
	s_waitcnt vmcnt(8)
	s_waitcnt lgkmcnt(0)
	s_setprio 1
	s_barrier
	v_mfma_f32_16x16x32_bf16 v[66:69], v[150:153], v[166:169], 0
	v_mfma_f32_16x16x32_bf16 v[66:69], v[154:157], v[170:173], v[66:69]
	v_mfma_f32_16x16x32_bf16 v[62:65], v[158:161], v[166:169], 0
	v_mfma_f32_16x16x32_bf16 v[62:65], v[162:165], v[170:173], v[62:65]
	v_mfma_f32_16x16x32_bf16 v[50:53], v[150:153], v[174:177], 0
	v_mfma_f32_16x16x32_bf16 v[50:53], v[154:157], v[178:181], v[50:53]
	v_mfma_f32_16x16x32_bf16 v[46:49], v[158:161], v[174:177], 0
	v_mfma_f32_16x16x32_bf16 v[46:49], v[162:165], v[178:181], v[46:49]
	v_mfma_f32_16x16x32_bf16 v[30:33], v[150:153], v[182:185], 0
	v_mfma_f32_16x16x32_bf16 v[30:33], v[154:157], v[186:189], v[30:33]
	v_mfma_f32_16x16x32_bf16 v[26:29], v[158:161], v[182:185], 0
	v_mfma_f32_16x16x32_bf16 v[26:29], v[162:165], v[186:189], v[26:29]
	v_mfma_f32_16x16x32_bf16 v[14:17], v[150:153], v[190:193], 0
	v_mfma_f32_16x16x32_bf16 v[14:17], v[154:157], v[194:197], v[14:17]
	v_mfma_f32_16x16x32_bf16 v[10:13], v[158:161], v[190:193], 0
	v_mfma_f32_16x16x32_bf16 v[10:13], v[162:165], v[194:197], v[10:13]
	v_mfma_f32_16x16x32_bf16 v[58:61], v[134:137], v[166:169], 0
	v_mfma_f32_16x16x32_bf16 v[58:61], v[138:141], v[170:173], v[58:61]
	v_mfma_f32_16x16x32_bf16 v[54:57], v[142:145], v[166:169], 0
	v_mfma_f32_16x16x32_bf16 v[54:57], v[146:149], v[170:173], v[54:57]
	v_mfma_f32_16x16x32_bf16 v[42:45], v[134:137], v[174:177], 0
	v_mfma_f32_16x16x32_bf16 v[42:45], v[138:141], v[178:181], v[42:45]
	v_mfma_f32_16x16x32_bf16 v[36:39], v[142:145], v[174:177], 0
	v_mfma_f32_16x16x32_bf16 v[36:39], v[146:149], v[178:181], v[36:39]
	v_mfma_f32_16x16x32_bf16 v[22:25], v[134:137], v[182:185], 0
	v_mfma_f32_16x16x32_bf16 v[22:25], v[138:141], v[186:189], v[22:25]
	v_mfma_f32_16x16x32_bf16 v[18:21], v[142:145], v[182:185], 0
	v_mfma_f32_16x16x32_bf16 v[18:21], v[146:149], v[186:189], v[18:21]
	v_mfma_f32_16x16x32_bf16 v[6:9], v[134:137], v[190:193], 0
	v_mfma_f32_16x16x32_bf16 v[6:9], v[138:141], v[194:197], v[6:9]
	v_mfma_f32_16x16x32_bf16 v[2:5], v[142:145], v[190:193], 0
	v_mfma_f32_16x16x32_bf16 v[2:5], v[146:149], v[194:197], v[2:5]
	s_barrier
	s_setprio 0
	s_add_i32 s78, 0, 0x18000
	v_add_u32_e32 v34, s78, v242
	s_add_i32 s79, 0, 0x1c000
	ds_read_b128 v[134:137], v34
	ds_read_b128 v[138:141], v34 offset:1024
	ds_read_b128 v[142:145], v34 offset:2048
	ds_read_b128 v[146:149], v34 offset:3072
	v_add_u32_e32 v34, s79, v242
	ds_read_b128 v[150:153], v34
	ds_read_b128 v[154:157], v34 offset:1024
	ds_read_b128 v[158:161], v34 offset:2048
	ds_read_b128 v[162:165], v34 offset:3072
	s_add_u32 s42, s42, 0x80000
	s_addc_u32 s43, s43, 0
	s_mov_b32 m0, s63
	v_lshl_add_u64 v[40:41], s[42:43], 0, v[208:209]
	ds_read_b128 v[166:169], v244 offset:32768
	ds_read_b128 v[170:173], v244 offset:33792
	ds_read_b128 v[174:177], v244 offset:34816
	ds_read_b128 v[178:181], v244 offset:35840
	ds_read_b128 v[182:185], v244 offset:36864
	ds_read_b128 v[186:189], v244 offset:37888
	ds_read_b128 v[190:193], v244 offset:38912
	ds_read_b128 v[194:197], v244 offset:39936
	global_load_lds_dwordx4 v[40:41], off
	v_lshl_add_u64 v[40:41], s[42:43], 0, v[212:213]
	s_mov_b32 m0, s64
	s_nop 0
	global_load_lds_dwordx4 v[40:41], off
	s_waitcnt vmcnt(8)
	s_waitcnt lgkmcnt(0)
	s_setprio 1
	s_barrier
	v_mfma_f32_16x16x32_bf16 v[130:133], v[134:137], v[166:169], v[130:133]
	v_mfma_f32_16x16x32_bf16 v[130:133], v[138:141], v[170:173], v[130:133]
	v_mfma_f32_16x16x32_bf16 v[126:129], v[142:145], v[166:169], v[126:129]
	v_mfma_f32_16x16x32_bf16 v[126:129], v[146:149], v[170:173], v[126:129]
	v_mfma_f32_16x16x32_bf16 v[114:117], v[134:137], v[174:177], v[114:117]
	v_mfma_f32_16x16x32_bf16 v[114:117], v[138:141], v[178:181], v[114:117]
	v_mfma_f32_16x16x32_bf16 v[110:113], v[142:145], v[174:177], v[110:113]
	v_mfma_f32_16x16x32_bf16 v[110:113], v[146:149], v[178:181], v[110:113]
	v_mfma_f32_16x16x32_bf16 v[98:101], v[134:137], v[182:185], v[98:101]
	v_mfma_f32_16x16x32_bf16 v[98:101], v[138:141], v[186:189], v[98:101]
	v_mfma_f32_16x16x32_bf16 v[94:97], v[142:145], v[182:185], v[94:97]
	v_mfma_f32_16x16x32_bf16 v[94:97], v[146:149], v[186:189], v[94:97]
	v_mfma_f32_16x16x32_bf16 v[82:85], v[134:137], v[190:193], v[82:85]
	v_mfma_f32_16x16x32_bf16 v[82:85], v[138:141], v[194:197], v[82:85]
	v_mfma_f32_16x16x32_bf16 v[78:81], v[142:145], v[190:193], v[78:81]
	v_mfma_f32_16x16x32_bf16 v[78:81], v[146:149], v[194:197], v[78:81]
	v_mfma_f32_16x16x32_bf16 v[122:125], v[150:153], v[166:169], v[122:125]
	v_mfma_f32_16x16x32_bf16 v[122:125], v[154:157], v[170:173], v[122:125]
	v_mfma_f32_16x16x32_bf16 v[118:121], v[158:161], v[166:169], v[118:121]
	v_mfma_f32_16x16x32_bf16 v[118:121], v[162:165], v[170:173], v[118:121]
	v_mfma_f32_16x16x32_bf16 v[106:109], v[150:153], v[174:177], v[106:109]
	v_mfma_f32_16x16x32_bf16 v[106:109], v[154:157], v[178:181], v[106:109]
	v_mfma_f32_16x16x32_bf16 v[102:105], v[158:161], v[174:177], v[102:105]
	v_mfma_f32_16x16x32_bf16 v[102:105], v[162:165], v[178:181], v[102:105]
	v_mfma_f32_16x16x32_bf16 v[90:93], v[150:153], v[182:185], v[90:93]
	v_mfma_f32_16x16x32_bf16 v[90:93], v[154:157], v[186:189], v[90:93]
	v_mfma_f32_16x16x32_bf16 v[86:89], v[158:161], v[182:185], v[86:89]
	v_mfma_f32_16x16x32_bf16 v[86:89], v[162:165], v[186:189], v[86:89]
	v_mfma_f32_16x16x32_bf16 v[74:77], v[150:153], v[190:193], v[74:77]
	v_mfma_f32_16x16x32_bf16 v[74:77], v[154:157], v[194:197], v[74:77]
	v_mfma_f32_16x16x32_bf16 v[70:73], v[158:161], v[190:193], v[70:73]
	v_mfma_f32_16x16x32_bf16 v[70:73], v[162:165], v[194:197], v[70:73]
	s_barrier
	s_setprio 0
	s_add_i32 s42, s78, s52
	v_lshl_add_u64 v[40:41], v[198:199], 0, s[18:19]
	s_mov_b32 m0, s42
	ds_read_b128 v[166:169], v244 offset:49152
	ds_read_b128 v[170:173], v244 offset:50176
	ds_read_b128 v[174:177], v244 offset:51200
	ds_read_b128 v[178:181], v244 offset:52224
	ds_read_b128 v[182:185], v244 offset:53248
	ds_read_b128 v[186:189], v244 offset:54272
	ds_read_b128 v[190:193], v244 offset:55296
	ds_read_b128 v[194:197], v244 offset:56320
	global_load_lds_dwordx4 v[40:41], off
	s_add_i32 m0, s42, 0x2000
	s_add_u32 s40, s40, 0x80080
	v_lshl_add_u64 v[40:41], v[200:201], 0, s[18:19]
	s_addc_u32 s41, s41, 0
	s_add_i32 s42, s79, s52
	global_load_lds_dwordx4 v[40:41], off
	v_lshl_add_u64 v[40:41], s[40:41], 0, v[210:211]
	s_mov_b32 m0, s42
	s_nop 0
	global_load_lds_dwordx4 v[40:41], off
	v_lshl_add_u64 v[40:41], s[40:41], 0, v[214:215]
	s_add_i32 m0, s42, 0x2000
	s_nop 0
	global_load_lds_dwordx4 v[40:41], off
	v_lshl_add_u64 v[40:41], v[246:247], 0, s[18:19]
	s_mov_b32 m0, s65
	s_nop 0
	global_load_lds_dwordx4 v[40:41], off
	v_lshl_add_u64 v[40:41], v[248:249], 0, s[18:19]
	s_mov_b32 m0, s66
	s_nop 0
	global_load_lds_dwordx4 v[40:41], off
	s_waitcnt vmcnt(8)
	s_waitcnt lgkmcnt(0)
	s_setprio 1
	s_barrier
	v_mfma_f32_16x16x32_bf16 v[66:69], v[134:137], v[166:169], v[66:69]
	v_mfma_f32_16x16x32_bf16 v[66:69], v[138:141], v[170:173], v[66:69]
	v_mfma_f32_16x16x32_bf16 v[62:65], v[142:145], v[166:169], v[62:65]
	v_mfma_f32_16x16x32_bf16 v[62:65], v[146:149], v[170:173], v[62:65]
	v_mfma_f32_16x16x32_bf16 v[50:53], v[134:137], v[174:177], v[50:53]
	v_mfma_f32_16x16x32_bf16 v[50:53], v[138:141], v[178:181], v[50:53]
	v_mfma_f32_16x16x32_bf16 v[46:49], v[142:145], v[174:177], v[46:49]
	v_mfma_f32_16x16x32_bf16 v[46:49], v[146:149], v[178:181], v[46:49]
	v_mfma_f32_16x16x32_bf16 v[30:33], v[134:137], v[182:185], v[30:33]
	v_mfma_f32_16x16x32_bf16 v[30:33], v[138:141], v[186:189], v[30:33]
	v_mfma_f32_16x16x32_bf16 v[26:29], v[142:145], v[182:185], v[26:29]
	v_mfma_f32_16x16x32_bf16 v[26:29], v[146:149], v[186:189], v[26:29]
	v_mfma_f32_16x16x32_bf16 v[14:17], v[134:137], v[190:193], v[14:17]
	v_mfma_f32_16x16x32_bf16 v[14:17], v[138:141], v[194:197], v[14:17]
	v_mfma_f32_16x16x32_bf16 v[10:13], v[142:145], v[190:193], v[10:13]
	v_mfma_f32_16x16x32_bf16 v[10:13], v[146:149], v[194:197], v[10:13]
	v_mfma_f32_16x16x32_bf16 v[58:61], v[150:153], v[166:169], v[58:61]
	v_mfma_f32_16x16x32_bf16 v[58:61], v[154:157], v[170:173], v[58:61]
	v_mfma_f32_16x16x32_bf16 v[54:57], v[158:161], v[166:169], v[54:57]
	v_mfma_f32_16x16x32_bf16 v[54:57], v[162:165], v[170:173], v[54:57]
	v_mfma_f32_16x16x32_bf16 v[40:43], v[150:153], v[174:177], v[42:45]
	v_mfma_f32_16x16x32_bf16 v[42:45], v[154:157], v[178:181], v[40:43]
	v_mfma_f32_16x16x32_bf16 v[36:39], v[158:161], v[174:177], v[36:39]
	v_mfma_f32_16x16x32_bf16 v[38:41], v[162:165], v[178:181], v[36:39]
	v_mfma_f32_16x16x32_bf16 v[22:25], v[150:153], v[182:185], v[22:25]
	v_mfma_f32_16x16x32_bf16 v[22:25], v[154:157], v[186:189], v[22:25]
	v_mfma_f32_16x16x32_bf16 v[18:21], v[158:161], v[182:185], v[18:21]
	v_mfma_f32_16x16x32_bf16 v[18:21], v[162:165], v[186:189], v[18:21]
	v_mfma_f32_16x16x32_bf16 v[6:9], v[150:153], v[190:193], v[6:9]
	v_mfma_f32_16x16x32_bf16 v[6:9], v[154:157], v[194:197], v[6:9]
	v_mfma_f32_16x16x32_bf16 v[2:5], v[158:161], v[190:193], v[2:5]
	v_mfma_f32_16x16x32_bf16 v[2:5], v[162:165], v[194:197], v[2:5]
	s_barrier
	s_setprio 0
	s_add_i32 vcc_lo, vcc_lo, 2
	s_add_u32 s36, s36, 0x100
	s_addc_u32 s37, s37, 0
	s_cmp_gt_u32 vcc_lo, 29
	s_cbranch_scc0 .LBB0_1644
	s_branch .LBB0_1648
.LPO_wout:
	s_add_i32 m0, s54, 0x21200
	s_nop 0
	global_load_lds_dwordx4 v[222:223], off
	s_branch .LPO_1643
.LBB0_1644:
	s_cmpk_lg_i32 s36, 0x800
	s_cbranch_scc1 .LBB0_1646
	v_add_u32_e32 v34, s67, v243
	ds_read_b128 v[134:137], v34
	ds_read_b128 v[138:141], v34 offset:16
	s_waitcnt lgkmcnt(0)
	v_mov_b32_e32 v36, v134
	v_mov_b32_e32 v37, v138
	v_mov_b32_e32 v138, v135
	v_mov_b32_e32 v134, v136
	v_mov_b32_e32 v135, v140
	v_mov_b32_e32 v140, v137
	v_pk_add_f32 v[36:37], v[36:37], v[138:139]
	v_pk_add_f32 v[134:135], v[134:135], v[140:141]
	s_nop 0
	v_pk_add_f32 v[36:37], v[36:37], v[134:135]
	s_nop 0
	v_add_f32_e32 v34, v36, v37
	v_add_u32_e32 v36, s68, v243
	ds_read_b128 v[134:137], v36
	ds_read_b128 v[138:141], v36 offset:16
	v_fmamk_f32 v34, v34, 0x3a800000, v1
	v_sqrt_f32_e32 v34, v34
	s_waitcnt lgkmcnt(0)
	v_mov_b32_e32 v36, v134
	v_mov_b32_e32 v37, v138
	v_mov_b32_e32 v138, v135
	v_mov_b32_e32 v134, v136
	v_mov_b32_e32 v135, v140
	v_mov_b32_e32 v140, v137
	v_pk_add_f32 v[36:37], v[36:37], v[138:139]
	v_pk_add_f32 v[134:135], v[134:135], v[140:141]
	v_pk_mul_f32 v[132:133], v[132:133], v[34:35] op_sel_hi:[1,0]
	v_pk_add_f32 v[36:37], v[36:37], v[134:135]
	v_pk_mul_f32 v[130:131], v[130:131], v[34:35] op_sel_hi:[1,0]
	v_add_f32_e32 v36, v36, v37
	v_add_u32_e32 v37, s69, v243
	ds_read_b128 v[134:137], v37
	ds_read_b128 v[138:141], v37 offset:16
	v_fmamk_f32 v36, v36, 0x3a800000, v1
	v_sqrt_f32_e32 v36, v36
	v_pk_mul_f32 v[128:129], v[128:129], v[34:35] op_sel_hi:[1,0]
	s_waitcnt lgkmcnt(0)
	v_mov_b32_e32 v142, v134
	v_mov_b32_e32 v143, v138
	v_mov_b32_e32 v138, v135
	v_pk_add_f32 v[134:135], v[142:143], v[138:139]
	v_mov_b32_e32 v138, v136
	v_mov_b32_e32 v139, v140
	v_mov_b32_e32 v140, v137
	v_pk_add_f32 v[136:137], v[138:139], v[140:141]
	v_pk_mul_f32 v[116:117], v[116:117], v[36:37] op_sel_hi:[1,0]
	v_pk_add_f32 v[134:135], v[134:135], v[136:137]
	v_pk_mul_f32 v[114:115], v[114:115], v[36:37] op_sel_hi:[1,0]
	v_add_f32_e32 v37, v134, v135
	v_fmamk_f32 v37, v37, 0x3a800000, v1
	v_sqrt_f32_e32 v142, v37
	v_add_u32_e32 v37, s70, v243
	ds_read_b128 v[134:137], v37
	ds_read_b128 v[138:141], v37 offset:16
	v_pk_mul_f32 v[126:127], v[126:127], v[34:35] op_sel_hi:[1,0]
	v_pk_mul_f32 v[124:125], v[124:125], v[34:35] op_sel_hi:[1,0]
	v_pk_mul_f32 v[122:123], v[122:123], v[34:35] op_sel_hi:[1,0]
	s_waitcnt lgkmcnt(0)
	v_mov_b32_e32 v144, v134
	v_mov_b32_e32 v145, v138
	v_mov_b32_e32 v138, v135
	v_pk_add_f32 v[134:135], v[144:145], v[138:139]
	v_mov_b32_e32 v138, v136
	v_mov_b32_e32 v139, v140
	v_mov_b32_e32 v140, v137
	v_pk_add_f32 v[136:137], v[138:139], v[140:141]
	v_pk_mul_f32 v[120:121], v[120:121], v[34:35] op_sel_hi:[1,0]
	v_pk_add_f32 v[134:135], v[134:135], v[136:137]
	v_pk_mul_f32 v[118:119], v[118:119], v[34:35] op_sel_hi:[1,0]
	v_add_u32_e32 v34, s71, v243
	v_pk_mul_f32 v[112:113], v[112:113], v[36:37] op_sel_hi:[1,0]
	v_pk_mul_f32 v[110:111], v[110:111], v[36:37] op_sel_hi:[1,0]
	v_add_f32_e32 v37, v134, v135
	ds_read_b128 v[134:137], v34
	ds_read_b128 v[138:141], v34 offset:16
	v_fmamk_f32 v37, v37, 0x3a800000, v1
	v_sqrt_f32_e32 v144, v37
	v_pk_mul_f32 v[108:109], v[108:109], v[36:37] op_sel_hi:[1,0]
	v_pk_mul_f32 v[106:107], v[106:107], v[36:37] op_sel_hi:[1,0]
	v_pk_mul_f32 v[104:105], v[104:105], v[36:37] op_sel_hi:[1,0]
	v_pk_mul_f32 v[102:103], v[102:103], v[36:37] op_sel_hi:[1,0]
	s_waitcnt lgkmcnt(0)
	v_mov_b32_e32 v36, v134
	v_mov_b32_e32 v37, v138
	v_mov_b32_e32 v138, v135
	v_mov_b32_e32 v134, v136
	v_mov_b32_e32 v135, v140
	v_mov_b32_e32 v140, v137
	v_pk_add_f32 v[36:37], v[36:37], v[138:139]
	v_pk_add_f32 v[134:135], v[134:135], v[140:141]
	v_pk_mul_f32 v[100:101], v[100:101], v[142:143] op_sel_hi:[1,0]
	v_pk_add_f32 v[36:37], v[36:37], v[134:135]
	v_pk_mul_f32 v[98:99], v[98:99], v[142:143] op_sel_hi:[1,0]
	v_add_f32_e32 v34, v36, v37
	v_add_u32_e32 v36, s72, v243
	ds_read_b128 v[134:137], v36
	ds_read_b128 v[138:141], v36 offset:16
	v_fmamk_f32 v34, v34, 0x3a800000, v1
	v_sqrt_f32_e32 v34, v34
	v_pk_mul_f32 v[96:97], v[96:97], v[142:143] op_sel_hi:[1,0]
	s_waitcnt lgkmcnt(0)
	v_mov_b32_e32 v36, v134
	v_mov_b32_e32 v37, v138
	v_mov_b32_e32 v138, v135
	v_mov_b32_e32 v134, v136
	v_mov_b32_e32 v135, v140
	v_mov_b32_e32 v140, v137
	v_pk_mul_f32 v[68:69], v[68:69], v[34:35] op_sel_hi:[1,0]
	v_pk_mul_f32 v[66:67], v[66:67], v[34:35] op_sel_hi:[1,0]
	v_pk_mul_f32 v[64:65], v[64:65], v[34:35] op_sel_hi:[1,0]
	v_pk_mul_f32 v[62:63], v[62:63], v[34:35] op_sel_hi:[1,0]
	v_pk_mul_f32 v[60:61], v[60:61], v[34:35] op_sel_hi:[1,0]
	v_pk_add_f32 v[36:37], v[36:37], v[138:139]
	v_pk_add_f32 v[134:135], v[134:135], v[140:141]
	v_pk_mul_f32 v[58:59], v[58:59], v[34:35] op_sel_hi:[1,0]
	v_pk_mul_f32 v[56:57], v[56:57], v[34:35] op_sel_hi:[1,0]
	v_pk_mul_f32 v[54:55], v[54:55], v[34:35] op_sel_hi:[1,0]
	v_add_u32_e32 v34, s73, v243
	v_pk_add_f32 v[36:37], v[36:37], v[134:135]
	ds_read_b128 v[134:137], v34
	ds_read_b128 v[138:141], v34 offset:16
	v_add_f32_e32 v36, v36, v37
	v_fmamk_f32 v36, v36, 0x3a800000, v1
	v_sqrt_f32_e32 v36, v36
	v_pk_mul_f32 v[94:95], v[94:95], v[142:143] op_sel_hi:[1,0]
	v_pk_mul_f32 v[92:93], v[92:93], v[142:143] op_sel_hi:[1,0]
	v_pk_mul_f32 v[90:91], v[90:91], v[142:143] op_sel_hi:[1,0]
	v_pk_mul_f32 v[88:89], v[88:89], v[142:143] op_sel_hi:[1,0]
	v_pk_mul_f32 v[86:87], v[86:87], v[142:143] op_sel_hi:[1,0]
	s_waitcnt lgkmcnt(0)
	v_mov_b32_e32 v142, v134
	v_mov_b32_e32 v143, v138
	v_mov_b32_e32 v138, v135
	v_pk_add_f32 v[134:135], v[142:143], v[138:139]
	v_mov_b32_e32 v138, v136
	v_mov_b32_e32 v139, v140
	v_mov_b32_e32 v140, v137
	v_pk_add_f32 v[136:137], v[138:139], v[140:141]
	v_pk_mul_f32 v[52:53], v[52:53], v[36:37] op_sel_hi:[1,0]
	v_pk_mul_f32 v[50:51], v[50:51], v[36:37] op_sel_hi:[1,0]
	v_pk_mul_f32 v[48:49], v[48:49], v[36:37] op_sel_hi:[1,0]
	v_pk_mul_f32 v[46:47], v[46:47], v[36:37] op_sel_hi:[1,0]
	v_pk_mul_f32 v[44:45], v[44:45], v[36:37] op_sel_hi:[1,0]
	v_pk_add_f32 v[134:135], v[134:135], v[136:137]
	v_pk_mul_f32 v[42:43], v[42:43], v[36:37] op_sel_hi:[1,0]
	v_pk_mul_f32 v[40:41], v[40:41], v[36:37] op_sel_hi:[1,0]
	v_pk_mul_f32 v[38:39], v[38:39], v[36:37] op_sel_hi:[1,0]
	v_add_u32_e32 v36, s74, v243
	v_add_f32_e32 v34, v134, v135
	ds_read_b128 v[134:137], v36
	ds_read_b128 v[138:141], v36 offset:16
	v_fmamk_f32 v34, v34, 0x3a800000, v1
	v_sqrt_f32_e32 v34, v34
	v_pk_mul_f32 v[84:85], v[84:85], v[144:145] op_sel_hi:[1,0]
	s_waitcnt lgkmcnt(0)
	v_mov_b32_e32 v36, v134
	v_mov_b32_e32 v37, v138
	v_mov_b32_e32 v138, v135
	v_mov_b32_e32 v134, v136
	v_mov_b32_e32 v135, v140
	v_mov_b32_e32 v140, v137
	v_pk_add_f32 v[36:37], v[36:37], v[138:139]
	v_pk_add_f32 v[134:135], v[134:135], v[140:141]
	v_pk_mul_f32 v[82:83], v[82:83], v[144:145] op_sel_hi:[1,0]
	v_pk_add_f32 v[36:37], v[36:37], v[134:135]
	v_pk_mul_f32 v[80:81], v[80:81], v[144:145] op_sel_hi:[1,0]
	v_add_f32_e32 v36, v36, v37
	v_fmamk_f32 v36, v36, 0x3a800000, v1
	v_sqrt_f32_e32 v36, v36
	v_pk_mul_f32 v[78:79], v[78:79], v[144:145] op_sel_hi:[1,0]
	v_pk_mul_f32 v[76:77], v[76:77], v[144:145] op_sel_hi:[1,0]
	v_pk_mul_f32 v[74:75], v[74:75], v[144:145] op_sel_hi:[1,0]
	v_pk_mul_f32 v[72:73], v[72:73], v[144:145] op_sel_hi:[1,0]
	v_pk_mul_f32 v[70:71], v[70:71], v[144:145] op_sel_hi:[1,0]
	v_pk_mul_f32 v[32:33], v[32:33], v[34:35] op_sel_hi:[1,0]
	v_pk_mul_f32 v[30:31], v[30:31], v[34:35] op_sel_hi:[1,0]
	v_pk_mul_f32 v[28:29], v[28:29], v[34:35] op_sel_hi:[1,0]
	v_pk_mul_f32 v[26:27], v[26:27], v[34:35] op_sel_hi:[1,0]
	v_pk_mul_f32 v[24:25], v[24:25], v[34:35] op_sel_hi:[1,0]
	v_pk_mul_f32 v[22:23], v[22:23], v[34:35] op_sel_hi:[1,0]
	v_pk_mul_f32 v[20:21], v[20:21], v[34:35] op_sel_hi:[1,0]
	v_pk_mul_f32 v[18:19], v[18:19], v[34:35] op_sel_hi:[1,0]
	v_pk_mul_f32 v[16:17], v[16:17], v[36:37] op_sel_hi:[1,0]
	v_pk_mul_f32 v[14:15], v[14:15], v[36:37] op_sel_hi:[1,0]
	v_pk_mul_f32 v[12:13], v[12:13], v[36:37] op_sel_hi:[1,0]
	v_pk_mul_f32 v[10:11], v[10:11], v[36:37] op_sel_hi:[1,0]
	v_pk_mul_f32 v[8:9], v[8:9], v[36:37] op_sel_hi:[1,0]
	v_pk_mul_f32 v[6:7], v[6:7], v[36:37] op_sel_hi:[1,0]
	v_pk_mul_f32 v[4:5], v[4:5], v[36:37] op_sel_hi:[1,0]
	v_pk_mul_f32 v[2:3], v[2:3], v[36:37] op_sel_hi:[1,0]
